# softmax running-sum: dropped 7 dead low-half adds left over from the packed-add split
# baseline (speedup 1.0000x reference)
.Lfx_nv0_v:
	v_exp_f32_e32 v2, v0
	v_sub_f32_e32 v0, v81, v192
	v_exp_f32_e32 v0, v0
	v_add_f32_e32 v3, v193, v194
	v_add_f32_e32 v4, v2, v0
	v_add_f32_e32 v5, v3, v1
	s_nop 0
	v_add_f32_e32 v9, v4, v5
	v_sub_f32_e32 v3, v98, v192
	v_sub_f32_e32 v4, v82, v192
	v_exp_f32_e32 v3, v3
	v_exp_f32_e32 v98, v4
	v_sub_f32_e32 v4, v99, v192
	v_sub_f32_e32 v5, v83, v192
	v_exp_f32_e32 v4, v4
	v_exp_f32_e32 v8, v5
	v_add_f32_e32 v5, v3, v98
	v_cvt_pk_bf16_f32 v196, v193, v2
	v_cvt_pk_bf16_f32 v197, v3, v4
	v_add_f32_e32 v6, v4, v8
	v_add_f32_e32 v7, v5, v9
	v_sub_f32_e32 v5, v100, v192
	v_add_f32_e32 v11, v6, v7
	v_sub_f32_e32 v6, v84, v192
	v_exp_f32_e32 v5, v5
	v_exp_f32_e32 v9, v6
	v_sub_f32_e32 v6, v101, v192
	v_sub_f32_e32 v7, v85, v192
	v_exp_f32_e32 v6, v6
	v_exp_f32_e32 v10, v7
	s_cmp_lt_i32 s41, 1
	s_cbranch_scc1 .Lfx_nv1_v
	global_load_lds_dwordx4 v188, s[30:31] offset:2048
.Lfx_nv1_v:
	v_add_f32_e32 v7, v5, v9
	v_cvt_pk_bf16_f32 v198, v5, v6
	v_add_f32_e32 v12, v6, v10
	v_add_f32_e32 v13, v7, v11
	v_sub_f32_e32 v7, v102, v192
	v_add_f32_e32 v13, v12, v13
	v_sub_f32_e32 v11, v86, v192
	v_sub_f32_e32 v12, v103, v192
	v_exp_f32_e32 v7, v7
	v_exp_f32_e32 v11, v11
	v_exp_f32_e32 v14, v12
	v_sub_f32_e32 v12, v87, v192
	v_exp_f32_e32 v12, v12
	v_add_f32_e32 v15, v7, v11
	v_cvt_pk_bf16_f32 v199, v7, v14
	v_cvt_pk_bf16_f32 v200, v194, v0
	v_add_f32_e32 v80, v14, v12
	v_add_f32_e32 v81, v15, v13
	v_sub_f32_e32 v13, v104, v192
	v_add_f32_e32 v81, v80, v81
	v_sub_f32_e32 v15, v88, v192
	v_sub_f32_e32 v80, v105, v192
	v_exp_f32_e32 v13, v13
	v_exp_f32_e32 v15, v15
	v_exp_f32_e32 v82, v80
	v_sub_f32_e32 v80, v89, v192
	v_exp_f32_e32 v80, v80
	v_add_f32_e32 v83, v13, v15
	v_cvt_pk_bf16_f32 v201, v98, v8
	v_cvt_pk_bf16_f32 v202, v9, v10
	s_cmp_lt_i32 s41, 1
	s_cbranch_scc1 .Lfx_nv2_v
	global_load_lds_dwordx4 v188, s[30:31] offset:3072
.Lfx_nv2_v:
	v_add_f32_e32 v84, v82, v80
	v_add_f32_e32 v85, v83, v81
	v_sub_f32_e32 v81, v106, v192
	v_add_f32_e32 v85, v84, v85
	v_sub_f32_e32 v83, v90, v192
	v_sub_f32_e32 v84, v107, v192
	v_exp_f32_e32 v81, v81
	v_exp_f32_e32 v83, v83
	v_exp_f32_e32 v86, v84
	v_sub_f32_e32 v84, v91, v192
	v_exp_f32_e32 v84, v84
	v_add_f32_e32 v87, v81, v83
	v_cvt_pk_bf16_f32 v203, v11, v12
	v_cvt_pk_bf16_f32 v204, v13, v82
	v_add_f32_e32 v88, v86, v84
	v_add_f32_e32 v89, v87, v85
	v_sub_f32_e32 v85, v108, v192
	v_add_f32_e32 v89, v88, v89
	v_sub_f32_e32 v87, v92, v192
	v_sub_f32_e32 v88, v109, v192
	v_exp_f32_e32 v85, v85
	v_exp_f32_e32 v87, v87
	v_exp_f32_e32 v90, v88
	v_sub_f32_e32 v88, v93, v192
	v_exp_f32_e32 v88, v88
	v_add_f32_e32 v91, v85, v87
	v_cvt_pk_bf16_f32 v205, v81, v86
	v_cvt_pk_bf16_f32 v206, v85, v90
	v_add_f32_e32 v92, v90, v88
	v_add_f32_e32 v93, v91, v89
	v_sub_f32_e32 v89, v110, v192
	v_add_f32_e32 v93, v92, v93
	v_sub_f32_e32 v91, v94, v192
	v_sub_f32_e32 v92, v111, v192
	v_exp_f32_e32 v89, v89
	v_exp_f32_e32 v91, v91
	v_exp_f32_e32 v94, v92
	v_sub_f32_e32 v92, v95, v192
	v_exp_f32_e32 v92, v92
	v_add_f32_e32 v95, v89, v91
	v_cvt_pk_bf16_f32 v207, v89, v94
	v_cvt_pk_bf16_f32 v208, v15, v80
	v_add_f32_e32 v96, v94, v92
	v_add_f32_e32 v97, v95, v93
	v_cvt_pk_bf16_f32 v209, v83, v84
	v_add_f32_e32 v93, v96, v97
	v_add_f32_e32 v162, v162, v93
	v_cvt_pk_bf16_f32 v210, v87, v88
	v_cvt_pk_bf16_f32 v211, v91, v92
	s_cmp_lt_i32 s41, 1
	s_cbranch_scc1 .Lfx_w0_v
	s_waitcnt vmcnt(4)
	s_branch .Lfx_w1_v
